# split3 weight conversion schedule + small_gemm32 wave reduce via DPP (3 steps) instead of ds_bpermute
# baseline (speedup 1.0000x reference)
.LBB0_736:
	s_and_b32 s4, s6, 0xffffffc0
	s_addk_i32 s4, 0x4000
	v_or_b32_e32 v6, s4, v8
	v_ashrrev_i32_e32 v7, 31, v6
	v_lshlrev_b64 v[6:7], 11, v[6:7]
	v_lshl_add_u64 v[6:7], v[0:1], 0, v[6:7]
	v_add_co_u32_e32 v98, vcc, s73, v6
	s_mov_b32 s10, 0x14000
	s_nop 0
	v_addc_co_u32_e32 v99, vcc, 0, v7, vcc
	v_add_co_u32_e32 v102, vcc, s84, v6
	global_load_dwordx4 v[14:17], v[6:7], off
	s_nop 0
	v_addc_co_u32_e32 v103, vcc, 0, v7, vcc
	v_add_co_u32_e32 v106, vcc, s75, v6
	global_load_dwordx4 v[18:21], v[98:99], off
	s_nop 0
	v_addc_co_u32_e32 v107, vcc, 0, v7, vcc
	v_add_co_u32_e32 v94, vcc, s74, v6
	s_and_b32 s5, s7, 0x3e0
	s_nop 0
	v_addc_co_u32_e32 v95, vcc, 0, v7, vcc
	v_add_co_u32_e32 v90, vcc, s10, v6
	global_load_dwordx4 v[30:33], v[94:95], off
	s_nop 0
	v_addc_co_u32_e32 v91, vcc, 0, v7, vcc
	v_add_co_u32_e32 v86, vcc, s9, v6
	global_load_dwordx4 v[34:37], v[90:91], off
	s_nop 0
	v_addc_co_u32_e32 v87, vcc, 0, v7, vcc
	v_add_co_u32_e32 v82, vcc, s33, v6
	global_load_dwordx4 v[38:41], v[86:87], off
	s_nop 0
	v_addc_co_u32_e32 v83, vcc, 0, v7, vcc
	v_or_b32_e32 v5, s5, v8
	global_load_dwordx4 v[42:45], v[82:83], off
	v_lshlrev_b32_e32 v208, 11, v5
	v_lshl_add_u64 v[62:63], v[2:3], 0, v[208:209]
	global_load_dwordx4 v[22:25], v[102:103], off
	global_load_dwordx4 v[26:29], v[106:107], off
	v_add_co_u32_e32 v66, vcc, s75, v62
	s_lshl_b32 s92, s5, 1
	s_nop 0
	v_addc_co_u32_e32 v67, vcc, 0, v63, vcc
	v_add_co_u32_e32 v70, vcc, s84, v62
	v_mov_b32_e32 v5, v209
	s_nop 0
	v_addc_co_u32_e32 v71, vcc, 0, v63, vcc
	v_add_co_u32_e32 v74, vcc, s73, v62
	s_nop 1
	v_addc_co_u32_e32 v75, vcc, 0, v63, vcc
	global_load_dwordx4 v[46:49], v[62:63], off
	global_load_dwordx4 v[50:53], v[74:75], off
	global_load_dwordx4 v[54:57], v[70:71], off
	global_load_dwordx4 v[58:61], v[66:67], off
	s_nop 0
	global_load_dwordx4 v[62:65], v[62:63], off offset:128
	s_nop 0
	global_load_dwordx4 v[66:69], v[66:67], off offset:128
	s_nop 0
	global_load_dwordx4 v[70:73], v[70:71], off offset:128
	s_nop 0
	global_load_dwordx4 v[74:77], v[74:75], off offset:128
	s_nop 0
	global_load_dwordx4 v[78:81], v[6:7], off offset:128
	s_nop 0
	global_load_dwordx4 v[82:85], v[82:83], off offset:128
	s_nop 0
	global_load_dwordx4 v[86:89], v[86:87], off offset:128
	s_nop 0
	global_load_dwordx4 v[90:93], v[90:91], off offset:128
	s_nop 0
	global_load_dwordx4 v[94:97], v[94:95], off offset:128
	s_nop 0
	global_load_dwordx4 v[98:101], v[98:99], off offset:128
	s_nop 0
	global_load_dwordx4 v[102:105], v[102:103], off offset:128
	s_nop 0
	global_load_dwordx4 v[106:109], v[106:107], off offset:128
	v_add_u32_e32 v6, s4, v9
	v_ashrrev_i32_e32 v7, 31, v6
	s_waitcnt vmcnt(0)
	ds_write_b128 v11, v[14:17]
	ds_write_b128 v11, v[30:33] offset:4608
	ds_write_b128 v11, v[34:37] offset:5760
	ds_write_b128 v11, v[38:41] offset:6912
	ds_write_b128 v11, v[42:45] offset:8064
	ds_write_b128 v11, v[18:21] offset:1152
	ds_write_b128 v11, v[22:25] offset:2304
	ds_write_b128 v11, v[26:29] offset:3456
	ds_read_b128 v[14:17], v12
	ds_read_b128 v[18:21], v12 offset:64
	ds_read_b128 v[22:25], v12 offset:2304
	ds_read_b128 v[26:29], v12 offset:2368
	ds_read_b128 v[30:33], v12 offset:4608
	ds_read_b128 v[34:37], v12 offset:4672
	ds_read_b128 v[38:41], v12 offset:6912
	ds_read_b128 v[42:45], v12 offset:6976
	s_waitcnt lgkmcnt(0)
	ds_write_b128 v11, v[46:49]
	ds_write_b128 v11, v[50:53] offset:1152
	ds_write_b128 v11, v[54:57] offset:2304
	ds_write_b128 v11, v[58:61] offset:3456
	ds_read_b128 v[46:49], v12
	ds_read_b128 v[54:57], v12 offset:2304
	s_waitcnt lgkmcnt(1)
	v_mfma_f32_16x16x32_bf16 v[50:53], v[46:49], v[14:17], 0
	ds_read_b128 v[114:117], v12 offset:2368
	s_waitcnt lgkmcnt(1)
	v_mfma_f32_16x16x32_bf16 v[14:17], v[54:57], v[14:17], 0
	v_mfma_f32_16x16x32_bf16 v[58:61], v[46:49], v[22:25], 0
	v_mfma_f32_16x16x32_bf16 v[22:25], v[54:57], v[22:25], 0
	v_mfma_f32_16x16x32_bf16 v[110:113], v[46:49], v[30:33], 0
	v_mfma_f32_16x16x32_bf16 v[30:33], v[54:57], v[30:33], 0
	v_mfma_f32_16x16x32_bf16 v[46:49], v[46:49], v[38:41], 0
	v_mfma_f32_16x16x32_bf16 v[38:41], v[54:57], v[38:41], 0
	ds_read_b128 v[54:57], v12 offset:64
	s_waitcnt lgkmcnt(0)
	ds_write_b128 v11, v[78:81]
	ds_write_b128 v11, v[98:101] offset:1152
	ds_write_b128 v11, v[102:105] offset:2304
	ds_write_b128 v11, v[106:109] offset:3456
	ds_write_b128 v11, v[94:97] offset:4608
	ds_write_b128 v11, v[90:93] offset:5760
	ds_write_b128 v11, v[86:89] offset:6912
	ds_write_b128 v11, v[82:85] offset:8064
	s_waitcnt lgkmcnt(8)
	v_mfma_f32_16x16x32_bf16 v[50:53], v[54:57], v[18:21], v[50:53]
	v_mfma_f32_16x16x32_bf16 v[14:17], v[114:117], v[18:21], v[14:17]
	v_mfma_f32_16x16x32_bf16 v[18:21], v[54:57], v[26:29], v[58:61]
	v_mfma_f32_16x16x32_bf16 v[22:25], v[114:117], v[26:29], v[22:25]
	v_mfma_f32_16x16x32_bf16 v[26:29], v[54:57], v[34:37], v[110:113]
	v_mfma_f32_16x16x32_bf16 v[30:33], v[114:117], v[34:37], v[30:33]
	v_mfma_f32_16x16x32_bf16 v[34:37], v[54:57], v[42:45], v[46:49]
	v_mfma_f32_16x16x32_bf16 v[38:41], v[114:117], v[42:45], v[38:41]
	ds_read_b128 v[42:45], v12
	s_nop 0
	ds_read_b128 v[46:49], v12 offset:64
	ds_read_b128 v[54:57], v12 offset:2304
	ds_read_b128 v[58:61], v12 offset:2368
	ds_read_b128 v[78:81], v12 offset:4608
	ds_read_b128 v[82:85], v12 offset:4672
	ds_read_b128 v[86:89], v12 offset:6912
	ds_read_b128 v[90:93], v12 offset:6976
	s_waitcnt lgkmcnt(0)
	ds_write_b128 v11, v[62:65]
	ds_write_b128 v11, v[74:77] offset:1152
	ds_write_b128 v11, v[70:73] offset:2304
	ds_write_b128 v11, v[66:69] offset:3456
	ds_read_b128 v[62:65], v12
	ds_read_b128 v[66:69], v12 offset:2304
	s_waitcnt lgkmcnt(1)
	v_mfma_f32_16x16x32_bf16 v[50:53], v[62:65], v[42:45], v[50:53]
	s_waitcnt lgkmcnt(0)
	v_mfma_f32_16x16x32_bf16 v[14:17], v[66:69], v[42:45], v[14:17]
	ds_read_b128 v[42:45], v12 offset:64
	v_mfma_f32_16x16x32_bf16 v[18:21], v[62:65], v[54:57], v[18:21]
	v_mfma_f32_16x16x32_bf16 v[22:25], v[66:69], v[54:57], v[22:25]
	ds_read_b128 v[54:57], v12 offset:2368
	s_waitcnt lgkmcnt(0)
	s_waitcnt lgkmcnt(0)
	v_mfma_f32_16x16x32_bf16 v[26:29], v[62:65], v[78:81], v[26:29]
	s_barrier
	v_mfma_f32_16x16x32_bf16 v[30:33], v[66:69], v[78:81], v[30:33]
	v_mfma_f32_16x16x32_bf16 v[34:37], v[62:65], v[86:89], v[34:37]
	v_mfma_f32_16x16x32_bf16 v[38:41], v[66:69], v[86:89], v[38:41]
	v_mfma_f32_16x16x32_bf16 v[50:53], v[42:45], v[46:49], v[50:53]
	v_mfma_f32_16x16x32_bf16 v[14:17], v[54:57], v[46:49], v[14:17]
	v_mfma_f32_16x16x32_bf16 v[18:21], v[42:45], v[58:61], v[18:21]
	v_mfma_f32_16x16x32_bf16 v[22:25], v[54:57], v[58:61], v[22:25]
	v_mfma_f32_16x16x32_bf16 v[26:29], v[42:45], v[82:85], v[26:29]
	v_mfma_f32_16x16x32_bf16 v[30:33], v[54:57], v[82:85], v[30:33]
	v_mfma_f32_16x16x32_bf16 v[34:37], v[42:45], v[90:93], v[34:37]
	v_mfma_f32_16x16x32_bf16 v[38:41], v[54:57], v[90:93], v[38:41]
	s_nop 0
	ds_write_b128 v13, v[50:53]
	ds_write_b128 v13, v[14:17] offset:64
	ds_write_b128 v13, v[18:21] offset:2304
	ds_write_b128 v13, v[22:25] offset:2368
	ds_write_b128 v13, v[26:29] offset:4608
	ds_write_b128 v13, v[30:33] offset:4672
	ds_write_b128 v13, v[34:37] offset:6912
	ds_write_b128 v13, v[38:41] offset:6976
	v_lshlrev_b64 v[14:15], 11, v[6:7]
	v_lshl_add_u64 v[14:15], s[46:47], 0, v[14:15]
	v_lshl_add_u64 v[14:15], v[14:15], 0, s[92:93]
	v_lshl_add_u64 v[28:29], v[14:15], 0, v[4:5]
	s_waitcnt lgkmcnt(0)
	s_barrier
	global_load_dwordx2 v[30:31], v[28:29], off
	ds_read_b128 v[14:17], v10
	ds_read_b128 v[18:21], v10 offset:9216
	ds_read_b128 v[22:25], v10 offset:18432
	s_waitcnt lgkmcnt(2)
	v_pk_add_f32 v[16:17], v[16:17], 0 op_sel_hi:[1,0]
	v_pk_add_f32 v[26:27], v[14:15], 0 op_sel_hi:[1,0]
	s_waitcnt lgkmcnt(1)
	v_pk_add_f32 v[20:21], v[16:17], v[20:21]
	ds_read_b128 v[14:17], v10 offset:27648
	v_pk_add_f32 v[26:27], v[26:27], v[18:19]
	s_waitcnt lgkmcnt(1)
	v_pk_add_f32 v[24:25], v[20:21], v[24:25]
	ds_read_b128 v[18:21], v10 offset:36864
	v_pk_add_f32 v[22:23], v[26:27], v[22:23]
	s_waitcnt lgkmcnt(1)
	v_pk_add_f32 v[24:25], v[24:25], v[16:17]
	v_pk_add_f32 v[26:27], v[22:23], v[14:15]
	ds_read_b128 v[14:17], v10 offset:46080
	s_waitcnt lgkmcnt(1)
	v_pk_add_f32 v[32:33], v[24:25], v[20:21]
	ds_read_b128 v[20:23], v10 offset:55296
	v_pk_add_f32 v[18:19], v[26:27], v[18:19]
	ds_read_b128 v[24:27], v10 offset:64512
	s_waitcnt lgkmcnt(2)
	v_pk_add_f32 v[14:15], v[18:19], v[14:15]
	v_pk_add_f32 v[16:17], v[32:33], v[16:17]
	s_waitcnt lgkmcnt(1)
	v_pk_add_f32 v[14:15], v[14:15], v[20:21]
	v_pk_add_f32 v[16:17], v[16:17], v[22:23]
	s_waitcnt lgkmcnt(0)
	v_pk_add_f32 v[14:15], v[14:15], v[24:25]
	v_pk_add_f32 v[16:17], v[16:17], v[26:27]
	s_waitcnt vmcnt(0)
	v_lshlrev_b32_e32 v18, 16, v30
	v_and_b32_e32 v19, 0xffff0000, v30
	v_pk_add_f32 v[18:19], v[14:15], v[18:19]
	v_lshlrev_b32_e32 v14, 16, v31
	v_and_b32_e32 v15, 0xffff0000, v31
	v_pk_add_f32 v[16:17], v[16:17], v[14:15]
	v_pk_mul_f32 v[14:15], v[18:19], v[18:19]
	v_pk_mul_f32 v[20:21], v[16:17], v[16:17]
	v_add_f32_e32 v5, v14, v15
	v_add_f32_e32 v14, v20, v21
	v_and_b32_e32 v15, 64, v230
	v_add_f32_e32 v5, v5, v14
	v_xor_b32_e32 v14, 1, v230
	v_add_u32_e32 v15, 64, v15
	v_cmp_lt_i32_e32 vcc, v14, v15
	v_cvt_pk_bf16_f32 v18, v18, v19
	v_cvt_pk_bf16_f32 v19, v16, v17
	v_cndmask_b32_e32 v14, v230, v14, vcc
	v_lshlrev_b32_e32 v14, 2, v14
	s_nop 1
	v_mov_b32_dpp v14, v5 quad_perm:[1,0,3,2] row_mask:0xf bank_mask:0xf
	global_store_dwordx2 v[28:29], v[18:19], off
	s_waitcnt lgkmcnt(0)
	v_add_f32_e32 v5, v5, v14
	v_xor_b32_e32 v14, 2, v230
	v_cmp_lt_i32_e32 vcc, v14, v15
	s_nop 1
	v_cndmask_b32_e32 v14, v230, v14, vcc
	v_lshlrev_b32_e32 v14, 2, v14
	s_nop 1
	v_mov_b32_dpp v14, v5 quad_perm:[2,3,0,1] row_mask:0xf bank_mask:0xf
	s_waitcnt lgkmcnt(0)
	v_add_f32_e32 v5, v5, v14
	v_xor_b32_e32 v14, 4, v230
	v_cmp_lt_i32_e32 vcc, v14, v15
	s_nop 1
	v_cndmask_b32_e32 v14, v230, v14, vcc
	v_lshlrev_b32_e32 v14, 2, v14
	s_nop 1
	v_mov_b32_dpp v14, v5 row_half_mirror row_mask:0xf bank_mask:0xf
	s_and_saveexec_b64 s[4:5], s[0:1]
	s_cbranch_execz .LBB0_735
	s_waitcnt lgkmcnt(0)
	v_add_f32_e32 v5, v5, v14
	v_lshl_add_u64 v[6:7], v[6:7], 2, s[76:77]
	global_atomic_add_f32 v[6:7], v5, off
	s_branch .LBB0_735

.LBB0_901:
	s_barrier
	ds_write_b128 v199, v[96:99]
	ds_write_b128 v199, v[100:103] offset:64
	ds_write_b128 v199, v[104:107] offset:2304
	ds_write_b128 v199, v[108:111] offset:2368
	ds_write_b128 v199, v[112:115] offset:4608
	ds_write_b128 v199, v[116:119] offset:4672
	ds_write_b128 v199, v[120:123] offset:6912
	ds_write_b128 v199, v[124:127] offset:6976
	s_waitcnt lgkmcnt(0)
	s_barrier
	s_waitcnt vmcnt(11)
	ds_read_b128 v[0:3], v196
	s_lshl_b32 s92, s15, 1
	v_mov_b32_e32 v185, v209
	s_waitcnt vmcnt(10) lgkmcnt(0)
	v_pk_add_f32 v[4:5], v[2:3], 0 op_sel_hi:[1,0]
	v_pk_add_f32 v[6:7], v[0:1], 0 op_sel_hi:[1,0]
	ds_read_b128 v[0:3], v196 offset:9216
	s_waitcnt lgkmcnt(0)
	v_pk_add_f32 v[4:5], v[4:5], v[2:3]
	v_pk_add_f32 v[6:7], v[6:7], v[0:1]
	ds_read_b128 v[0:3], v196 offset:18432
	s_waitcnt lgkmcnt(0)
	v_pk_add_f32 v[4:5], v[4:5], v[2:3]
	v_pk_add_f32 v[6:7], v[6:7], v[0:1]
	ds_read_b128 v[0:3], v196 offset:27648
	s_waitcnt lgkmcnt(0)
	v_pk_add_f32 v[4:5], v[4:5], v[2:3]
	v_pk_add_f32 v[6:7], v[6:7], v[0:1]
	ds_read_b128 v[0:3], v196 offset:36864
	s_waitcnt lgkmcnt(0)
	v_pk_add_f32 v[4:5], v[4:5], v[2:3]
	v_pk_add_f32 v[6:7], v[6:7], v[0:1]
	ds_read_b128 v[0:3], v196 offset:46080
	s_waitcnt lgkmcnt(0)
	v_pk_add_f32 v[4:5], v[4:5], v[2:3]
	v_pk_add_f32 v[6:7], v[6:7], v[0:1]
	ds_read_b128 v[0:3], v196 offset:55296
	s_waitcnt lgkmcnt(0)
	v_pk_add_f32 v[4:5], v[4:5], v[2:3]
	v_pk_add_f32 v[6:7], v[6:7], v[0:1]
	ds_read_b128 v[0:3], v196 offset:64512
	s_waitcnt lgkmcnt(0)
	v_pk_add_f32 v[2:3], v[4:5], v[2:3]
	v_pk_add_f32 v[4:5], v[6:7], v[0:1]
	v_add_u32_e32 v0, s14, v195
	v_ashrrev_i32_e32 v1, 31, v0
	v_lshlrev_b64 v[6:7], 11, v[0:1]
	v_lshl_add_u64 v[6:7], s[46:47], 0, v[6:7]
	v_lshl_add_u64 v[6:7], v[6:7], 0, s[92:93]
	v_lshl_add_u64 v[6:7], v[6:7], 0, v[184:185]
	global_load_dwordx2 v[8:9], v[6:7], off
	s_waitcnt vmcnt(0)
	v_lshlrev_b32_e32 v10, 16, v8
	v_and_b32_e32 v11, 0xffff0000, v8
	v_lshlrev_b32_e32 v8, 16, v9
	v_and_b32_e32 v9, 0xffff0000, v9
	v_pk_add_f32 v[4:5], v[4:5], v[10:11]
	v_pk_add_f32 v[2:3], v[2:3], v[8:9]
	v_pk_mul_f32 v[8:9], v[4:5], v[4:5]
	v_pk_mul_f32 v[10:11], v[2:3], v[2:3]
	v_cvt_pk_bf16_f32 v4, v4, v5
	v_cvt_pk_bf16_f32 v5, v2, v3
	v_and_b32_e32 v3, 64, v230
	v_xor_b32_e32 v2, 1, v230
	v_add_u32_e32 v3, 64, v3
	v_cmp_lt_i32_e32 vcc, v2, v3
	v_add_f32_e32 v8, v8, v9
	v_add_f32_e32 v9, v10, v11
	v_cndmask_b32_e32 v2, v230, v2, vcc
	v_add_f32_e32 v8, v8, v9
	v_lshlrev_b32_e32 v2, 2, v2
	s_nop 1
	v_mov_b32_dpp v2, v8 quad_perm:[1,0,3,2] row_mask:0xf bank_mask:0xf
	global_store_dwordx2 v[6:7], v[4:5], off
	v_xor_b32_e32 v4, 2, v230
	v_cmp_lt_i32_e32 vcc, v4, v3
	s_waitcnt lgkmcnt(0)
	v_add_f32_e32 v2, v8, v2
	v_cndmask_b32_e32 v4, v230, v4, vcc
	v_lshlrev_b32_e32 v4, 2, v4
	s_nop 1
	v_mov_b32_dpp v4, v2 quad_perm:[2,3,0,1] row_mask:0xf bank_mask:0xf
	s_waitcnt lgkmcnt(0)
	v_add_f32_e32 v2, v2, v4
	v_xor_b32_e32 v4, 4, v230
	v_cmp_lt_i32_e32 vcc, v4, v3
	s_nop 1
	v_cndmask_b32_e32 v3, v230, v4, vcc
	v_lshlrev_b32_e32 v3, 2, v3
	s_nop 1
	v_mov_b32_dpp v3, v2 row_half_mirror row_mask:0xf bank_mask:0xf
	s_and_saveexec_b64 s[6:7], s[0:1]
	s_cbranch_execz .LBB0_894
	s_waitcnt lgkmcnt(0)
	v_add_f32_e32 v2, v2, v3
	v_lshl_add_u64 v[0:1], v[0:1], 2, s[12:13]
	global_atomic_add_f32 v[0:1], v2, off
	s_branch .LBB0_894
